# speedup vs baseline: 1.0054x; 1.0054x over previous
; DI u32 fkey(float f) { u32 u = __float_as_uint(f); return (u & 0x80000000u) ? ~u : (u | 0x80000000u); }
; DI void indexer_item(const Params& p, int b, int qt16, char* smem) {
;     ...
;     const int q = wid * 2 + qq;
;     const int t = t0 + q;
;     u64* mrow = p.MASK + ((long)b * SEQ + t) * 64;
;     if (t < 256) {
;       const int r = lane;
;       u64 w;
;       if (64 * r + 63 <= t) w = ~0ull;
;       else if (64 * r > t) w = 0ull;
;       else w = (~0ull) >> (63 - (t - 64 * r));
;       mrow[r] = w;
;       continue;
;     }
;     const float* srow = scr + (long)q * SEQ;
;     u32 u[64];
; #pragma unroll
;     for (int r = 0; r < 64; ++r) {
;       const int key = 64 * r + lane;
;       u[r] = (key <= t) ? fkey(srow[key]) : 0u;
;     }
.LBB0_324:
	v_or_b32_e32 v104, s0, v7
	v_add_u32_e32 v102, v104, v99
	s_movk_i32 s0, 0xff
	v_cmp_lt_i32_e32 vcc, s0, v102
	s_and_saveexec_b64 s[0:1], vcc
	s_xor_b64 s[90:91], exec, s[0:1]
	s_cbranch_execz .LBB0_966
	v_ashrrev_i32_e32 v105, 31, v104
	v_lshlrev_b64 v[104:105], 14, v[104:105]
	v_lshl_add_u64 v[104:105], s[96:97], 0, v[104:105]
	v_lshl_add_u64 v[106:107], v[104:105], 0, v[0:1]
	global_load_dword v3, v[106:107], off
	global_load_dword v109, v[106:107], off offset:256
	global_load_dword v5, v[106:107], off offset:512
	global_load_dword v108, v[106:107], off offset:768
	global_load_dword v141, v[106:107], off offset:1024
	global_load_dword v142, v[106:107], off offset:1280
	global_load_dword v143, v[106:107], off offset:1536
	global_load_dword v144, v[106:107], off offset:1792
	global_load_dword v145, v[106:107], off offset:2048
	global_load_dword v146, v[106:107], off offset:2304
	global_load_dword v147, v[106:107], off offset:2560
	global_load_dword v148, v[106:107], off offset:2816
	global_load_dword v149, v[106:107], off offset:3072
	global_load_dword v150, v[106:107], off offset:3328
	global_load_dword v151, v[106:107], off offset:3584
	global_load_dword v152, v[106:107], off offset:3840
	v_lshlrev_b32_e32 v246, 2, v2
	v_mov_b32_e32 v247, v1
	v_lshl_add_u64 v[246:247], v[104:105], 0, v[246:247]
	global_load_dword v153, v[246:247], off
	v_lshlrev_b32_e32 v246, 2, v4
	v_mov_b32_e32 v247, v1
	v_lshl_add_u64 v[246:247], v[104:105], 0, v[246:247]
	global_load_dword v154, v[246:247], off
	v_lshlrev_b32_e32 v246, 2, v6
	v_mov_b32_e32 v247, v1
	v_lshl_add_u64 v[246:247], v[104:105], 0, v[246:247]
	global_load_dword v155, v[246:247], off
	v_lshlrev_b32_e32 v246, 2, v8
	v_mov_b32_e32 v247, v1
	v_lshl_add_u64 v[246:247], v[104:105], 0, v[246:247]
	global_load_dword v156, v[246:247], off
	v_lshlrev_b32_e32 v246, 2, v10
	v_mov_b32_e32 v247, v1
	v_lshl_add_u64 v[246:247], v[104:105], 0, v[246:247]
	global_load_dword v157, v[246:247], off
	v_lshlrev_b32_e32 v246, 2, v12
	v_mov_b32_e32 v247, v1
	v_lshl_add_u64 v[246:247], v[104:105], 0, v[246:247]
	global_load_dword v158, v[246:247], off
	v_lshlrev_b32_e32 v246, 2, v14
	v_mov_b32_e32 v247, v1
	v_lshl_add_u64 v[246:247], v[104:105], 0, v[246:247]
	global_load_dword v159, v[246:247], off
	v_lshlrev_b32_e32 v246, 2, v16
	v_mov_b32_e32 v247, v1
	v_lshl_add_u64 v[246:247], v[104:105], 0, v[246:247]
	global_load_dword v160, v[246:247], off
	v_lshlrev_b32_e32 v246, 2, v18
	v_mov_b32_e32 v247, v1
	v_lshl_add_u64 v[246:247], v[104:105], 0, v[246:247]
	global_load_dword v161, v[246:247], off
	v_lshlrev_b32_e32 v246, 2, v20
	v_mov_b32_e32 v247, v1
	v_lshl_add_u64 v[246:247], v[104:105], 0, v[246:247]
	global_load_dword v162, v[246:247], off
	v_lshlrev_b32_e32 v246, 2, v22
	v_mov_b32_e32 v247, v1
	v_lshl_add_u64 v[246:247], v[104:105], 0, v[246:247]
	global_load_dword v163, v[246:247], off
	v_lshlrev_b32_e32 v246, 2, v24
	v_mov_b32_e32 v247, v1
	v_lshl_add_u64 v[246:247], v[104:105], 0, v[246:247]
	global_load_dword v164, v[246:247], off
	v_lshlrev_b32_e32 v246, 2, v26
	v_mov_b32_e32 v247, v1
	v_lshl_add_u64 v[246:247], v[104:105], 0, v[246:247]
	global_load_dword v165, v[246:247], off
	v_lshlrev_b32_e32 v246, 2, v28
	v_mov_b32_e32 v247, v1
	v_lshl_add_u64 v[246:247], v[104:105], 0, v[246:247]
	global_load_dword v166, v[246:247], off
	v_lshlrev_b32_e32 v246, 2, v30
	v_mov_b32_e32 v247, v1
	v_lshl_add_u64 v[246:247], v[104:105], 0, v[246:247]
	global_load_dword v167, v[246:247], off
	v_lshlrev_b32_e32 v246, 2, v32
	v_mov_b32_e32 v247, v1
	v_lshl_add_u64 v[246:247], v[104:105], 0, v[246:247]
	global_load_dword v168, v[246:247], off
	v_lshlrev_b32_e32 v246, 2, v34
	v_mov_b32_e32 v247, v1
	v_lshl_add_u64 v[246:247], v[104:105], 0, v[246:247]
	global_load_dword v169, v[246:247], off
	v_lshlrev_b32_e32 v246, 2, v36
	v_mov_b32_e32 v247, v1
	v_lshl_add_u64 v[246:247], v[104:105], 0, v[246:247]
	global_load_dword v170, v[246:247], off
	v_lshlrev_b32_e32 v246, 2, v38
	v_mov_b32_e32 v247, v1
	v_lshl_add_u64 v[246:247], v[104:105], 0, v[246:247]
	global_load_dword v171, v[246:247], off
	v_lshlrev_b32_e32 v246, 2, v40
	v_mov_b32_e32 v247, v1
	v_lshl_add_u64 v[246:247], v[104:105], 0, v[246:247]
	global_load_dword v172, v[246:247], off
	v_cmp_le_i32_e32 vcc, v13, v102
	v_mov_b32_e32 v39, 0
	v_mov_b32_e32 v41, 0
	s_and_saveexec_b64 s[0:1], vcc
	s_cbranch_execz .LBB0_327
	s_waitcnt vmcnt(31)
	v_mov_b32_e32 v37, v141
	v_not_b32_e32 v41, v37
	v_or_b32_e32 v43, 0x80000000, v37
	v_cmp_gt_i32_e32 vcc, 0, v37
	s_nop 1
	v_cndmask_b32_e32 v41, v43, v41, vcc
.LBB0_327:
	s_or_b64 exec, exec, s[0:1]
	v_cmp_le_i32_e32 vcc, v15, v102
	s_and_saveexec_b64 s[0:1], vcc
	s_cbranch_execz .LBB0_329
	s_waitcnt vmcnt(30)
	v_mov_b32_e32 v37, v142
	v_not_b32_e32 v39, v37
	v_or_b32_e32 v43, 0x80000000, v37
	v_cmp_gt_i32_e32 vcc, 0, v37
	s_nop 1
	v_cndmask_b32_e32 v39, v43, v39, vcc
.LBB0_329:
	s_or_b64 exec, exec, s[0:1]
	v_cmp_le_i32_e32 vcc, v17, v102
	v_mov_b32_e32 v37, 0
	v_mov_b32_e32 v47, 0
	s_and_saveexec_b64 s[0:1], vcc
	s_cbranch_execz .LBB0_331
	s_waitcnt vmcnt(29)
	v_mov_b32_e32 v43, v143
	v_not_b32_e32 v45, v43
	v_or_b32_e32 v47, 0x80000000, v43
	v_cmp_gt_i32_e32 vcc, 0, v43
	s_nop 1
	v_cndmask_b32_e32 v47, v47, v45, vcc
.LBB0_331:
	s_or_b64 exec, exec, s[0:1]
	v_cmp_le_i32_e32 vcc, v19, v102
	s_and_saveexec_b64 s[0:1], vcc
	s_cbranch_execz .LBB0_333
	s_waitcnt vmcnt(28)
	v_mov_b32_e32 v37, v144
	v_not_b32_e32 v43, v37
	v_or_b32_e32 v45, 0x80000000, v37
	v_cmp_gt_i32_e32 vcc, 0, v37
	s_nop 1
	v_cndmask_b32_e32 v37, v45, v43, vcc
; DI u32 fkey(float f) { u32 u = __float_as_uint(f); return (u & 0x80000000u) ? ~u : (u | 0x80000000u); }
; DI void indexer_item(const Params& p, int b, int qt16, char* smem) {
;     ...
;     const float* srow = scr + (long)q * SEQ;
;     u32 u[64];
; #pragma unroll
;     for (int r = 0; r < 64; ++r) {
;       const int key = 64 * r + lane;
;       u[r] = (key <= t) ? fkey(srow[key]) : 0u;
;     }
.LBB0_333:
	s_or_b64 exec, exec, s[0:1]
	v_cmp_le_i32_e32 vcc, v21, v102
	v_mov_b32_e32 v43, 0
	v_mov_b32_e32 v45, 0
	s_and_saveexec_b64 s[0:1], vcc
	s_cbranch_execz .LBB0_335
	s_waitcnt vmcnt(27)
	v_mov_b32_e32 v45, v145
	v_not_b32_e32 v49, v45
	v_or_b32_e32 v51, 0x80000000, v45
	v_cmp_gt_i32_e32 vcc, 0, v45
	s_nop 1
	v_cndmask_b32_e32 v45, v51, v49, vcc
.LBB0_335:
	s_or_b64 exec, exec, s[0:1]
	v_cmp_le_i32_e32 vcc, v23, v102
	s_and_saveexec_b64 s[0:1], vcc
	s_cbranch_execz .LBB0_337
	s_waitcnt vmcnt(26)
	v_mov_b32_e32 v43, v146
	v_not_b32_e32 v49, v43
	v_or_b32_e32 v51, 0x80000000, v43
	v_cmp_gt_i32_e32 vcc, 0, v43
	s_nop 1
	v_cndmask_b32_e32 v43, v51, v49, vcc
.LBB0_337:
	s_or_b64 exec, exec, s[0:1]
	v_cmp_le_i32_e32 vcc, v25, v102
	v_mov_b32_e32 v49, 0
	v_mov_b32_e32 v51, 0
	s_and_saveexec_b64 s[0:1], vcc
	s_cbranch_execz .LBB0_339
	s_waitcnt vmcnt(25)
	v_mov_b32_e32 v51, v147
	v_not_b32_e32 v53, v51
	v_or_b32_e32 v55, 0x80000000, v51
	v_cmp_gt_i32_e32 vcc, 0, v51
	s_nop 1
	v_cndmask_b32_e32 v51, v55, v53, vcc
.LBB0_339:
	s_or_b64 exec, exec, s[0:1]
	v_cmp_le_i32_e32 vcc, v27, v102
	s_and_saveexec_b64 s[0:1], vcc
	s_cbranch_execz .LBB0_341
	s_waitcnt vmcnt(24)
	v_mov_b32_e32 v49, v148
	v_not_b32_e32 v53, v49
	v_or_b32_e32 v55, 0x80000000, v49
	v_cmp_gt_i32_e32 vcc, 0, v49
	s_nop 1
	v_cndmask_b32_e32 v49, v55, v53, vcc
.LBB0_341:
	s_or_b64 exec, exec, s[0:1]
	v_cmp_le_i32_e32 vcc, v29, v102
	v_mov_b32_e32 v55, 0
	v_mov_b32_e32 v57, 0
	s_and_saveexec_b64 s[0:1], vcc
	s_cbranch_execz .LBB0_343
	s_waitcnt vmcnt(23)
	v_mov_b32_e32 v53, v149
	v_not_b32_e32 v57, v53
	v_or_b32_e32 v59, 0x80000000, v53
	v_cmp_gt_i32_e32 vcc, 0, v53
	s_nop 1
	v_cndmask_b32_e32 v57, v59, v57, vcc
.LBB0_343:
	s_or_b64 exec, exec, s[0:1]
	v_cmp_le_i32_e32 vcc, v31, v102
	s_and_saveexec_b64 s[0:1], vcc
	s_cbranch_execz .LBB0_345
	s_waitcnt vmcnt(22)
	v_mov_b32_e32 v53, v150
	v_not_b32_e32 v55, v53
	v_or_b32_e32 v59, 0x80000000, v53
	v_cmp_gt_i32_e32 vcc, 0, v53
	s_nop 1
	v_cndmask_b32_e32 v55, v59, v55, vcc
.LBB0_345:
	s_or_b64 exec, exec, s[0:1]
	v_cmp_le_i32_e32 vcc, v33, v102
	v_mov_b32_e32 v53, 0
	v_mov_b32_e32 v63, 0
	s_and_saveexec_b64 s[0:1], vcc
	s_cbranch_execz .LBB0_347
	s_waitcnt vmcnt(21)
	v_mov_b32_e32 v59, v151
	v_not_b32_e32 v61, v59
	v_or_b32_e32 v63, 0x80000000, v59
	v_cmp_gt_i32_e32 vcc, 0, v59
	s_nop 1
	v_cndmask_b32_e32 v63, v63, v61, vcc
.LBB0_347:
	s_or_b64 exec, exec, s[0:1]
	v_cmp_le_i32_e32 vcc, v35, v102
	s_and_saveexec_b64 s[0:1], vcc
	s_cbranch_execz .LBB0_349
	s_waitcnt vmcnt(20)
	v_mov_b32_e32 v53, v152
	v_not_b32_e32 v59, v53
	v_or_b32_e32 v61, 0x80000000, v53
	v_cmp_gt_i32_e32 vcc, 0, v53
	s_nop 1
	v_cndmask_b32_e32 v53, v61, v59, vcc
.LBB0_349:
	s_or_b64 exec, exec, s[0:1]
	v_cmp_le_i32_e32 vcc, v2, v102
	v_mov_b32_e32 v59, 0
	v_mov_b32_e32 v61, 0
	s_and_saveexec_b64 s[0:1], vcc
	s_cbranch_execz .LBB0_351
	v_lshlrev_b32_e32 v106, 2, v2
	v_mov_b32_e32 v107, v1
	v_lshl_add_u64 v[106:107], v[104:105], 0, v[106:107]
	s_waitcnt vmcnt(19)
	v_mov_b32_e32 v61, v153
	v_not_b32_e32 v65, v61
	v_or_b32_e32 v67, 0x80000000, v61
	v_cmp_gt_i32_e32 vcc, 0, v61
	s_nop 1
	v_cndmask_b32_e32 v61, v67, v65, vcc
.LBB0_351:
	s_or_b64 exec, exec, s[0:1]
	v_cmp_le_i32_e32 vcc, v4, v102
	s_and_saveexec_b64 s[0:1], vcc
	s_cbranch_execz .LBB0_353
	v_lshlrev_b32_e32 v106, 2, v4
	v_mov_b32_e32 v107, v1
	v_lshl_add_u64 v[106:107], v[104:105], 0, v[106:107]
	s_waitcnt vmcnt(18)
	v_mov_b32_e32 v59, v154
	v_not_b32_e32 v65, v59
	v_or_b32_e32 v67, 0x80000000, v59
	v_cmp_gt_i32_e32 vcc, 0, v59
	s_nop 1
	v_cndmask_b32_e32 v59, v67, v65, vcc
.LBB0_353:
	s_or_b64 exec, exec, s[0:1]
	v_cmp_le_i32_e32 vcc, v6, v102
	v_mov_b32_e32 v65, 0
	v_mov_b32_e32 v67, 0
	s_and_saveexec_b64 s[0:1], vcc
	s_cbranch_execz .LBB0_355
	v_lshlrev_b32_e32 v106, 2, v6
	v_mov_b32_e32 v107, v1
	v_lshl_add_u64 v[106:107], v[104:105], 0, v[106:107]
	s_waitcnt vmcnt(17)
	v_mov_b32_e32 v67, v155
	v_not_b32_e32 v69, v67
	v_or_b32_e32 v71, 0x80000000, v67
	v_cmp_gt_i32_e32 vcc, 0, v67
	s_nop 1
	v_cndmask_b32_e32 v67, v71, v69, vcc
.LBB0_355:
	s_or_b64 exec, exec, s[0:1]
	v_cmp_le_i32_e32 vcc, v8, v102
	s_and_saveexec_b64 s[0:1], vcc
	s_cbranch_execz .LBB0_357
	v_lshlrev_b32_e32 v106, 2, v8
	v_mov_b32_e32 v107, v1
	v_lshl_add_u64 v[106:107], v[104:105], 0, v[106:107]
	s_waitcnt vmcnt(16)
	v_mov_b32_e32 v65, v156
	v_not_b32_e32 v69, v65
	v_or_b32_e32 v71, 0x80000000, v65
	v_cmp_gt_i32_e32 vcc, 0, v65
	s_nop 1
	v_cndmask_b32_e32 v65, v71, v69, vcc
; DI u32 fkey(float f) { u32 u = __float_as_uint(f); return (u & 0x80000000u) ? ~u : (u | 0x80000000u); }
; DI void indexer_item(const Params& p, int b, int qt16, char* smem) {
;     ...
;     const float* srow = scr + (long)q * SEQ;
;     u32 u[64];
; #pragma unroll
;     for (int r = 0; r < 64; ++r) {
;       const int key = 64 * r + lane;
;       u[r] = (key <= t) ? fkey(srow[key]) : 0u;
;     }
.LBB0_357:
	s_or_b64 exec, exec, s[0:1]
	s_waitcnt vmcnt(16)
	v_lshlrev_b32_e32 v246, 2, v42
	v_mov_b32_e32 v247, v1
	v_lshl_add_u64 v[246:247], v[104:105], 0, v[246:247]
	global_load_dword v173, v[246:247], off
	v_lshlrev_b32_e32 v246, 2, v44
	v_mov_b32_e32 v247, v1
	v_lshl_add_u64 v[246:247], v[104:105], 0, v[246:247]
	global_load_dword v174, v[246:247], off
	v_lshlrev_b32_e32 v246, 2, v46
	v_mov_b32_e32 v247, v1
	v_lshl_add_u64 v[246:247], v[104:105], 0, v[246:247]
	global_load_dword v175, v[246:247], off
	v_lshlrev_b32_e32 v246, 2, v48
	v_mov_b32_e32 v247, v1
	v_lshl_add_u64 v[246:247], v[104:105], 0, v[246:247]
	global_load_dword v176, v[246:247], off
	v_lshlrev_b32_e32 v246, 2, v50
	v_mov_b32_e32 v247, v1
	v_lshl_add_u64 v[246:247], v[104:105], 0, v[246:247]
	global_load_dword v177, v[246:247], off
	v_lshlrev_b32_e32 v246, 2, v52
	v_mov_b32_e32 v247, v1
	v_lshl_add_u64 v[246:247], v[104:105], 0, v[246:247]
	global_load_dword v178, v[246:247], off
	v_lshlrev_b32_e32 v246, 2, v54
	v_mov_b32_e32 v247, v1
	v_lshl_add_u64 v[246:247], v[104:105], 0, v[246:247]
	global_load_dword v179, v[246:247], off
	v_lshlrev_b32_e32 v246, 2, v56
	v_mov_b32_e32 v247, v1
	v_lshl_add_u64 v[246:247], v[104:105], 0, v[246:247]
	global_load_dword v180, v[246:247], off
	v_lshlrev_b32_e32 v246, 2, v58
	v_mov_b32_e32 v247, v1
	v_lshl_add_u64 v[246:247], v[104:105], 0, v[246:247]
	global_load_dword v181, v[246:247], off
	v_lshlrev_b32_e32 v246, 2, v60
	v_mov_b32_e32 v247, v1
	v_lshl_add_u64 v[246:247], v[104:105], 0, v[246:247]
	global_load_dword v182, v[246:247], off
	v_lshlrev_b32_e32 v246, 2, v62
	v_mov_b32_e32 v247, v1
	v_lshl_add_u64 v[246:247], v[104:105], 0, v[246:247]
	global_load_dword v183, v[246:247], off
	v_lshlrev_b32_e32 v246, 2, v64
	v_mov_b32_e32 v247, v1
	v_lshl_add_u64 v[246:247], v[104:105], 0, v[246:247]
	global_load_dword v184, v[246:247], off
	v_lshlrev_b32_e32 v246, 2, v66
	v_mov_b32_e32 v247, v1
	v_lshl_add_u64 v[246:247], v[104:105], 0, v[246:247]
	global_load_dword v185, v[246:247], off
	v_lshlrev_b32_e32 v246, 2, v68
	v_mov_b32_e32 v247, v1
	v_lshl_add_u64 v[246:247], v[104:105], 0, v[246:247]
	global_load_dword v186, v[246:247], off
	v_lshlrev_b32_e32 v246, 2, v70
	v_mov_b32_e32 v247, v1
	v_lshl_add_u64 v[246:247], v[104:105], 0, v[246:247]
	global_load_dword v187, v[246:247], off
	v_lshlrev_b32_e32 v246, 2, v72
	v_mov_b32_e32 v247, v1
	v_lshl_add_u64 v[246:247], v[104:105], 0, v[246:247]
	global_load_dword v198, v[246:247], off
	v_lshlrev_b32_e32 v246, 2, v74
	v_mov_b32_e32 v247, v1
	v_lshl_add_u64 v[246:247], v[104:105], 0, v[246:247]
	global_load_dword v199, v[246:247], off
	v_lshlrev_b32_e32 v246, 2, v76
	v_mov_b32_e32 v247, v1
	v_lshl_add_u64 v[246:247], v[104:105], 0, v[246:247]
	global_load_dword v200, v[246:247], off
	v_lshlrev_b32_e32 v246, 2, v78
	v_mov_b32_e32 v247, v1
	v_lshl_add_u64 v[246:247], v[104:105], 0, v[246:247]
	global_load_dword v201, v[246:247], off
	v_lshlrev_b32_e32 v246, 2, v80
	v_mov_b32_e32 v247, v1
	v_lshl_add_u64 v[246:247], v[104:105], 0, v[246:247]
	global_load_dword v202, v[246:247], off
	v_lshlrev_b32_e32 v246, 2, v82
	v_mov_b32_e32 v247, v1
	v_lshl_add_u64 v[246:247], v[104:105], 0, v[246:247]
	global_load_dword v203, v[246:247], off
	v_lshlrev_b32_e32 v246, 2, v84
	v_mov_b32_e32 v247, v1
	v_lshl_add_u64 v[246:247], v[104:105], 0, v[246:247]
	global_load_dword v204, v[246:247], off
	v_lshlrev_b32_e32 v246, 2, v88
	v_mov_b32_e32 v247, v1
	v_lshl_add_u64 v[246:247], v[104:105], 0, v[246:247]
	global_load_dword v205, v[246:247], off
	v_lshlrev_b32_e32 v246, 2, v90
	v_mov_b32_e32 v247, v1
	v_lshl_add_u64 v[246:247], v[104:105], 0, v[246:247]
	global_load_dword v206, v[246:247], off
	v_lshlrev_b32_e32 v246, 2, v92
	v_mov_b32_e32 v247, v1
	v_lshl_add_u64 v[246:247], v[104:105], 0, v[246:247]
	global_load_dword v207, v[246:247], off
	v_lshlrev_b32_e32 v246, 2, v94
	v_mov_b32_e32 v247, v1
	v_lshl_add_u64 v[246:247], v[104:105], 0, v[246:247]
	global_load_dword v210, v[246:247], off
	v_lshlrev_b32_e32 v246, 2, v96
	v_mov_b32_e32 v247, v1
	v_lshl_add_u64 v[246:247], v[104:105], 0, v[246:247]
	global_load_dword v211, v[246:247], off
	v_lshlrev_b32_e32 v246, 2, v98
	v_mov_b32_e32 v247, v1
	v_lshl_add_u64 v[246:247], v[104:105], 0, v[246:247]
	global_load_dword v212, v[246:247], off
	v_cmp_le_i32_e32 vcc, v10, v102
	v_mov_b32_e32 v71, 0
	v_mov_b32_e32 v73, 0
	s_and_saveexec_b64 s[0:1], vcc
	s_cbranch_execz .LBB0_359
	v_lshlrev_b32_e32 v106, 2, v10
	v_mov_b32_e32 v107, v1
	v_lshl_add_u64 v[106:107], v[104:105], 0, v[106:107]
	s_waitcnt vmcnt(43)
	v_mov_b32_e32 v69, v157
	v_not_b32_e32 v73, v69
	v_or_b32_e32 v75, 0x80000000, v69
	v_cmp_gt_i32_e32 vcc, 0, v69
	s_nop 1
	v_cndmask_b32_e32 v73, v75, v73, vcc
.LBB0_359:
	s_or_b64 exec, exec, s[0:1]
	v_cmp_le_i32_e32 vcc, v12, v102
	s_and_saveexec_b64 s[0:1], vcc
	s_cbranch_execz .LBB0_361
	v_lshlrev_b32_e32 v106, 2, v12
	v_mov_b32_e32 v107, v1
	v_lshl_add_u64 v[106:107], v[104:105], 0, v[106:107]
	s_waitcnt vmcnt(42)
	v_mov_b32_e32 v69, v158
	v_not_b32_e32 v71, v69
	v_or_b32_e32 v75, 0x80000000, v69
	v_cmp_gt_i32_e32 vcc, 0, v69
	s_nop 1
	v_cndmask_b32_e32 v71, v75, v71, vcc
.LBB0_361:
	s_or_b64 exec, exec, s[0:1]
	v_cmp_le_i32_e32 vcc, v14, v102
	v_mov_b32_e32 v69, 0
	v_mov_b32_e32 v79, 0
	s_and_saveexec_b64 s[0:1], vcc
	s_cbranch_execz .LBB0_363
	v_lshlrev_b32_e32 v106, 2, v14
	v_mov_b32_e32 v107, v1
	v_lshl_add_u64 v[106:107], v[104:105], 0, v[106:107]
	s_waitcnt vmcnt(41)
	v_mov_b32_e32 v75, v159
	v_not_b32_e32 v77, v75
	v_or_b32_e32 v79, 0x80000000, v75
	v_cmp_gt_i32_e32 vcc, 0, v75
	s_nop 1
	v_cndmask_b32_e32 v79, v79, v77, vcc
; DI u32 fkey(float f) { u32 u = __float_as_uint(f); return (u & 0x80000000u) ? ~u : (u | 0x80000000u); }
; DI void indexer_item(const Params& p, int b, int qt16, char* smem) {
;     ...
;     const float* srow = scr + (long)q * SEQ;
;     u32 u[64];
; #pragma unroll
;     for (int r = 0; r < 64; ++r) {
;       const int key = 64 * r + lane;
;       u[r] = (key <= t) ? fkey(srow[key]) : 0u;
;     }
.LBB0_363:
	s_or_b64 exec, exec, s[0:1]
	v_cmp_le_i32_e32 vcc, v16, v102
	s_and_saveexec_b64 s[0:1], vcc
	s_cbranch_execz .LBB0_365
	v_lshlrev_b32_e32 v106, 2, v16
	v_mov_b32_e32 v107, v1
	v_lshl_add_u64 v[106:107], v[104:105], 0, v[106:107]
	s_waitcnt vmcnt(40)
	v_mov_b32_e32 v69, v160
	v_not_b32_e32 v75, v69
	v_or_b32_e32 v77, 0x80000000, v69
	v_cmp_gt_i32_e32 vcc, 0, v69
	s_nop 1
	v_cndmask_b32_e32 v69, v77, v75, vcc
.LBB0_365:
	s_or_b64 exec, exec, s[0:1]
	v_cmp_le_i32_e32 vcc, v18, v102
	v_mov_b32_e32 v75, 0
	v_mov_b32_e32 v77, 0
	s_and_saveexec_b64 s[0:1], vcc
	s_cbranch_execz .LBB0_367
	v_lshlrev_b32_e32 v106, 2, v18
	v_mov_b32_e32 v107, v1
	v_lshl_add_u64 v[106:107], v[104:105], 0, v[106:107]
	s_waitcnt vmcnt(39)
	v_mov_b32_e32 v77, v161
	v_not_b32_e32 v81, v77
	v_or_b32_e32 v83, 0x80000000, v77
	v_cmp_gt_i32_e32 vcc, 0, v77
	s_nop 1
	v_cndmask_b32_e32 v77, v83, v81, vcc
.LBB0_367:
	s_or_b64 exec, exec, s[0:1]
	v_cmp_le_i32_e32 vcc, v20, v102
	s_and_saveexec_b64 s[0:1], vcc
	s_cbranch_execz .LBB0_369
	v_lshlrev_b32_e32 v106, 2, v20
	v_mov_b32_e32 v107, v1
	v_lshl_add_u64 v[106:107], v[104:105], 0, v[106:107]
	s_waitcnt vmcnt(38)
	v_mov_b32_e32 v75, v162
	v_not_b32_e32 v81, v75
	v_or_b32_e32 v83, 0x80000000, v75
	v_cmp_gt_i32_e32 vcc, 0, v75
	s_nop 1
	v_cndmask_b32_e32 v75, v83, v81, vcc
.LBB0_369:
	s_or_b64 exec, exec, s[0:1]
	v_cmp_le_i32_e32 vcc, v22, v102
	v_mov_b32_e32 v81, 0
	v_mov_b32_e32 v83, 0
	s_and_saveexec_b64 s[0:1], vcc
	s_cbranch_execz .LBB0_371
	v_lshlrev_b32_e32 v106, 2, v22
	v_mov_b32_e32 v107, v1
	v_lshl_add_u64 v[106:107], v[104:105], 0, v[106:107]
	s_waitcnt vmcnt(37)
	v_mov_b32_e32 v83, v163
	v_not_b32_e32 v85, v83
	v_or_b32_e32 v89, 0x80000000, v83
	v_cmp_gt_i32_e32 vcc, 0, v83
	s_nop 1
	v_cndmask_b32_e32 v83, v89, v85, vcc
.LBB0_371:
	s_or_b64 exec, exec, s[0:1]
	v_cmp_le_i32_e32 vcc, v24, v102
	s_and_saveexec_b64 s[0:1], vcc
	s_cbranch_execz .LBB0_373
	v_lshlrev_b32_e32 v106, 2, v24
	v_mov_b32_e32 v107, v1
	v_lshl_add_u64 v[106:107], v[104:105], 0, v[106:107]
	s_waitcnt vmcnt(36)
	v_mov_b32_e32 v81, v164
	v_not_b32_e32 v85, v81
	v_or_b32_e32 v89, 0x80000000, v81
	v_cmp_gt_i32_e32 vcc, 0, v81
	s_nop 1
	v_cndmask_b32_e32 v81, v89, v85, vcc
.LBB0_373:
	s_or_b64 exec, exec, s[0:1]
	v_cmp_le_i32_e32 vcc, v26, v102
	v_mov_b32_e32 v89, 0
	v_mov_b32_e32 v91, 0
	s_and_saveexec_b64 s[0:1], vcc
	s_cbranch_execz .LBB0_375
	v_lshlrev_b32_e32 v106, 2, v26
	v_mov_b32_e32 v107, v1
	v_lshl_add_u64 v[106:107], v[104:105], 0, v[106:107]
	s_waitcnt vmcnt(35)
	v_mov_b32_e32 v85, v165
	v_not_b32_e32 v91, v85
	v_or_b32_e32 v93, 0x80000000, v85
	v_cmp_gt_i32_e32 vcc, 0, v85
	s_nop 1
	v_cndmask_b32_e32 v91, v93, v91, vcc
.LBB0_375:
	s_or_b64 exec, exec, s[0:1]
	v_cmp_le_i32_e32 vcc, v28, v102
	s_and_saveexec_b64 s[0:1], vcc
	s_cbranch_execz .LBB0_377
	v_lshlrev_b32_e32 v106, 2, v28
	v_mov_b32_e32 v107, v1
	v_lshl_add_u64 v[106:107], v[104:105], 0, v[106:107]
	s_waitcnt vmcnt(34)
	v_mov_b32_e32 v85, v166
	v_not_b32_e32 v89, v85
	v_or_b32_e32 v93, 0x80000000, v85
	v_cmp_gt_i32_e32 vcc, 0, v85
	s_nop 1
	v_cndmask_b32_e32 v89, v93, v89, vcc
.LBB0_377:
	s_or_b64 exec, exec, s[0:1]
	v_cmp_le_i32_e32 vcc, v30, v102
	v_mov_b32_e32 v85, 0
	v_mov_b32_e32 v97, 0
	s_and_saveexec_b64 s[0:1], vcc
	s_cbranch_execz .LBB0_379
	v_lshlrev_b32_e32 v106, 2, v30
	v_mov_b32_e32 v107, v1
	v_lshl_add_u64 v[106:107], v[104:105], 0, v[106:107]
	s_waitcnt vmcnt(33)
	v_mov_b32_e32 v93, v167
	v_not_b32_e32 v95, v93
	v_or_b32_e32 v97, 0x80000000, v93
	v_cmp_gt_i32_e32 vcc, 0, v93
	s_nop 1
	v_cndmask_b32_e32 v97, v97, v95, vcc
.LBB0_379:
	s_or_b64 exec, exec, s[0:1]
	v_cmp_le_i32_e32 vcc, v32, v102
	s_and_saveexec_b64 s[0:1], vcc
	s_cbranch_execz .LBB0_381
	v_lshlrev_b32_e32 v106, 2, v32
	v_mov_b32_e32 v107, v1
	v_lshl_add_u64 v[106:107], v[104:105], 0, v[106:107]
	s_waitcnt vmcnt(32)
	v_mov_b32_e32 v85, v168
	v_not_b32_e32 v93, v85
	v_or_b32_e32 v95, 0x80000000, v85
	v_cmp_gt_i32_e32 vcc, 0, v85
	s_nop 1
	v_cndmask_b32_e32 v85, v95, v93, vcc
.LBB0_381:
	s_or_b64 exec, exec, s[0:1]
	v_cmp_le_i32_e32 vcc, v34, v102
	v_mov_b32_e32 v93, 0
	v_mov_b32_e32 v95, 0
	s_and_saveexec_b64 s[0:1], vcc
	s_cbranch_execz .LBB0_383
	v_lshlrev_b32_e32 v106, 2, v34
	v_mov_b32_e32 v107, v1
	v_lshl_add_u64 v[106:107], v[104:105], 0, v[106:107]
	s_waitcnt vmcnt(31)
	v_mov_b32_e32 v95, v169
	v_not_b32_e32 v103, v95
	v_or_b32_e32 v106, 0x80000000, v95
	v_cmp_gt_i32_e32 vcc, 0, v95
	s_nop 1
	v_cndmask_b32_e32 v95, v106, v103, vcc
.LBB0_383:
	s_or_b64 exec, exec, s[0:1]
	v_cmp_le_i32_e32 vcc, v36, v102
	s_and_saveexec_b64 s[0:1], vcc
	s_cbranch_execz .LBB0_385
	v_lshlrev_b32_e32 v106, 2, v36
	v_mov_b32_e32 v107, v1
	v_lshl_add_u64 v[106:107], v[104:105], 0, v[106:107]
	s_waitcnt vmcnt(30)
	v_mov_b32_e32 v93, v170
	v_not_b32_e32 v103, v93
	v_or_b32_e32 v106, 0x80000000, v93
	v_cmp_gt_i32_e32 vcc, 0, v93
	s_nop 1
	v_cndmask_b32_e32 v93, v106, v103, vcc
.LBB0_385:
	s_or_b64 exec, exec, s[0:1]
	v_cmp_le_i32_e32 vcc, v38, v102
	v_mov_b32_e32 v103, 0
	v_mov_b32_e32 v107, 0
	s_and_saveexec_b64 s[0:1], vcc
	s_cbranch_execz .LBB0_387
	v_lshlrev_b32_e32 v106, 2, v38
	v_mov_b32_e32 v107, v1
	v_lshl_add_u64 v[106:107], v[104:105], 0, v[106:107]
	s_waitcnt vmcnt(29)
	v_mov_b32_e32 v106, v171
	v_not_b32_e32 v107, v106
	v_or_b32_e32 v110, 0x80000000, v106
	v_cmp_gt_i32_e32 vcc, 0, v106
	s_nop 1
	v_cndmask_b32_e32 v107, v110, v107, vcc
.LBB0_387:
	s_or_b64 exec, exec, s[0:1]
	v_cmp_le_i32_e32 vcc, v40, v102
	s_and_saveexec_b64 s[0:1], vcc
	s_cbranch_execz .LBB0_389
	v_lshlrev_b32_e32 v110, 2, v40
	v_mov_b32_e32 v111, v1
	v_lshl_add_u64 v[110:111], v[104:105], 0, v[110:111]
	s_waitcnt vmcnt(28)
	v_mov_b32_e32 v103, v172
	v_not_b32_e32 v106, v103
	v_or_b32_e32 v110, 0x80000000, v103
	v_cmp_gt_i32_e32 vcc, 0, v103
	s_nop 1
	v_cndmask_b32_e32 v103, v110, v106, vcc
; DI u32 fkey(float f) { u32 u = __float_as_uint(f); return (u & 0x80000000u) ? ~u : (u | 0x80000000u); }
; DI void indexer_item(const Params& p, int b, int qt16, char* smem) {
;     ...
;     const float* srow = scr + (long)q * SEQ;
;     u32 u[64];
; #pragma unroll
;     for (int r = 0; r < 64; ++r) {
;       const int key = 64 * r + lane;
;       u[r] = (key <= t) ? fkey(srow[key]) : 0u;
;     }
.LBB0_389:
	s_or_b64 exec, exec, s[0:1]
	v_cmp_le_i32_e32 vcc, v42, v102
	v_mov_b32_e32 v111, 0
	v_mov_b32_e32 v112, 0
	s_and_saveexec_b64 s[0:1], vcc
	s_cbranch_execz .LBB0_391
	v_lshlrev_b32_e32 v112, 2, v42
	v_mov_b32_e32 v113, v1
	v_lshl_add_u64 v[112:113], v[104:105], 0, v[112:113]
	s_waitcnt vmcnt(27)
	v_mov_b32_e32 v106, v173
	v_not_b32_e32 v110, v106
	v_or_b32_e32 v112, 0x80000000, v106
	v_cmp_gt_i32_e32 vcc, 0, v106
	s_nop 1
	v_cndmask_b32_e32 v112, v112, v110, vcc
.LBB0_391:
	s_or_b64 exec, exec, s[0:1]
	v_cmp_le_i32_e32 vcc, v44, v102
	s_and_saveexec_b64 s[0:1], vcc
	s_cbranch_execz .LBB0_393
	v_lshlrev_b32_e32 v110, 2, v44
	v_mov_b32_e32 v111, v1
	v_lshl_add_u64 v[110:111], v[104:105], 0, v[110:111]
	s_waitcnt vmcnt(26)
	v_mov_b32_e32 v106, v174
	v_not_b32_e32 v110, v106
	v_or_b32_e32 v111, 0x80000000, v106
	v_cmp_gt_i32_e32 vcc, 0, v106
	s_nop 1
	v_cndmask_b32_e32 v111, v111, v110, vcc
.LBB0_393:
	s_or_b64 exec, exec, s[0:1]
	v_cmp_le_i32_e32 vcc, v46, v102
	v_mov_b32_e32 v110, 0
	v_mov_b32_e32 v115, 0
	s_and_saveexec_b64 s[0:1], vcc
	s_cbranch_execz .LBB0_395
	v_lshlrev_b32_e32 v114, 2, v46
	v_mov_b32_e32 v115, v1
	v_lshl_add_u64 v[114:115], v[104:105], 0, v[114:115]
	s_waitcnt vmcnt(25)
	v_mov_b32_e32 v106, v175
	v_not_b32_e32 v113, v106
	v_or_b32_e32 v114, 0x80000000, v106
	v_cmp_gt_i32_e32 vcc, 0, v106
	s_nop 1
	v_cndmask_b32_e32 v115, v114, v113, vcc
.LBB0_395:
	s_or_b64 exec, exec, s[0:1]
	v_cmp_le_i32_e32 vcc, v48, v102
	s_and_saveexec_b64 s[0:1], vcc
	s_cbranch_execz .LBB0_397
	v_lshlrev_b32_e32 v116, 2, v48
	v_mov_b32_e32 v117, v1
	v_lshl_add_u64 v[116:117], v[104:105], 0, v[116:117]
	s_waitcnt vmcnt(24)
	v_mov_b32_e32 v106, v176
	v_not_b32_e32 v110, v106
	v_or_b32_e32 v113, 0x80000000, v106
	v_cmp_gt_i32_e32 vcc, 0, v106
	s_nop 1
	v_cndmask_b32_e32 v110, v113, v110, vcc
.LBB0_397:
	s_or_b64 exec, exec, s[0:1]
	v_cmp_le_i32_e32 vcc, v50, v102
	v_mov_b32_e32 v113, 0
	v_mov_b32_e32 v114, 0
	s_and_saveexec_b64 s[0:1], vcc
	s_cbranch_execz .LBB0_399
	v_lshlrev_b32_e32 v116, 2, v50
	v_mov_b32_e32 v117, v1
	v_lshl_add_u64 v[116:117], v[104:105], 0, v[116:117]
	s_waitcnt vmcnt(23)
	v_mov_b32_e32 v106, v177
	v_not_b32_e32 v114, v106
	v_or_b32_e32 v116, 0x80000000, v106
	v_cmp_gt_i32_e32 vcc, 0, v106
	s_nop 1
	v_cndmask_b32_e32 v114, v116, v114, vcc
.LBB0_399:
	s_or_b64 exec, exec, s[0:1]
	v_cmp_le_i32_e32 vcc, v52, v102
	s_and_saveexec_b64 s[0:1], vcc
	s_cbranch_execz .LBB0_401
	v_lshlrev_b32_e32 v116, 2, v52
	v_mov_b32_e32 v117, v1
	v_lshl_add_u64 v[116:117], v[104:105], 0, v[116:117]
	s_waitcnt vmcnt(22)
	v_mov_b32_e32 v106, v178
	v_not_b32_e32 v113, v106
	v_or_b32_e32 v116, 0x80000000, v106
	v_cmp_gt_i32_e32 vcc, 0, v106
	s_nop 1
	v_cndmask_b32_e32 v113, v116, v113, vcc
.LBB0_401:
	s_or_b64 exec, exec, s[0:1]
	v_cmp_le_i32_e32 vcc, v54, v102
	v_mov_b32_e32 v116, 0
	v_mov_b32_e32 v117, 0
	s_and_saveexec_b64 s[0:1], vcc
	s_cbranch_execz .LBB0_403
	v_lshlrev_b32_e32 v118, 2, v54
	v_mov_b32_e32 v119, v1
	v_lshl_add_u64 v[118:119], v[104:105], 0, v[118:119]
	s_waitcnt vmcnt(21)
	v_mov_b32_e32 v106, v179
	v_not_b32_e32 v117, v106
	v_or_b32_e32 v118, 0x80000000, v106
	v_cmp_gt_i32_e32 vcc, 0, v106
	s_nop 1
	v_cndmask_b32_e32 v117, v118, v117, vcc
.LBB0_403:
	s_or_b64 exec, exec, s[0:1]
	v_cmp_le_i32_e32 vcc, v56, v102
	s_and_saveexec_b64 s[0:1], vcc
	s_cbranch_execz .LBB0_405
	v_lshlrev_b32_e32 v118, 2, v56
	v_mov_b32_e32 v119, v1
	v_lshl_add_u64 v[118:119], v[104:105], 0, v[118:119]
	s_waitcnt vmcnt(20)
	v_mov_b32_e32 v106, v180
	v_not_b32_e32 v116, v106
	v_or_b32_e32 v118, 0x80000000, v106
	v_cmp_gt_i32_e32 vcc, 0, v106
	s_nop 1
	v_cndmask_b32_e32 v116, v118, v116, vcc
.LBB0_405:
	s_or_b64 exec, exec, s[0:1]
	v_cmp_le_i32_e32 vcc, v58, v102
	v_mov_b32_e32 v119, 0
	v_mov_b32_e32 v120, 0
	s_and_saveexec_b64 s[0:1], vcc
	s_cbranch_execz .LBB0_407
	v_lshlrev_b32_e32 v120, 2, v58
	v_mov_b32_e32 v121, v1
	v_lshl_add_u64 v[120:121], v[104:105], 0, v[120:121]
	s_waitcnt vmcnt(19)
	v_mov_b32_e32 v106, v181
	v_not_b32_e32 v118, v106
	v_or_b32_e32 v120, 0x80000000, v106
	v_cmp_gt_i32_e32 vcc, 0, v106
	s_nop 1
	v_cndmask_b32_e32 v120, v120, v118, vcc
.LBB0_407:
	s_or_b64 exec, exec, s[0:1]
	v_cmp_le_i32_e32 vcc, v60, v102
	s_and_saveexec_b64 s[0:1], vcc
	s_cbranch_execz .LBB0_409
	v_lshlrev_b32_e32 v118, 2, v60
	v_mov_b32_e32 v119, v1
	v_lshl_add_u64 v[118:119], v[104:105], 0, v[118:119]
	s_waitcnt vmcnt(18)
	v_mov_b32_e32 v106, v182
	v_not_b32_e32 v118, v106
	v_or_b32_e32 v119, 0x80000000, v106
	v_cmp_gt_i32_e32 vcc, 0, v106
	s_nop 1
	v_cndmask_b32_e32 v119, v119, v118, vcc
.LBB0_409:
	s_or_b64 exec, exec, s[0:1]
	v_cmp_le_i32_e32 vcc, v62, v102
	v_mov_b32_e32 v118, 0
	v_mov_b32_e32 v123, 0
	s_and_saveexec_b64 s[0:1], vcc
	s_cbranch_execz .LBB0_411
	v_lshlrev_b32_e32 v122, 2, v62
	v_mov_b32_e32 v123, v1
	v_lshl_add_u64 v[122:123], v[104:105], 0, v[122:123]
	s_waitcnt vmcnt(17)
	v_mov_b32_e32 v106, v183
	v_not_b32_e32 v121, v106
	v_or_b32_e32 v122, 0x80000000, v106
	v_cmp_gt_i32_e32 vcc, 0, v106
	s_nop 1
	v_cndmask_b32_e32 v123, v122, v121, vcc
.LBB0_411:
	s_or_b64 exec, exec, s[0:1]
	v_cmp_le_i32_e32 vcc, v64, v102
	s_and_saveexec_b64 s[0:1], vcc
	s_cbranch_execz .LBB0_413
	v_lshlrev_b32_e32 v124, 2, v64
	v_mov_b32_e32 v125, v1
	v_lshl_add_u64 v[124:125], v[104:105], 0, v[124:125]
	s_waitcnt vmcnt(16)
	v_mov_b32_e32 v106, v184
	v_not_b32_e32 v118, v106
	v_or_b32_e32 v121, 0x80000000, v106
	v_cmp_gt_i32_e32 vcc, 0, v106
	s_nop 1
	v_cndmask_b32_e32 v118, v121, v118, vcc
; DI u32 fkey(float f) { u32 u = __float_as_uint(f); return (u & 0x80000000u) ? ~u : (u | 0x80000000u); }
; DI void indexer_item(const Params& p, int b, int qt16, char* smem) {
;     ...
;     const float* srow = scr + (long)q * SEQ;
;     u32 u[64];
; #pragma unroll
;     for (int r = 0; r < 64; ++r) {
;       const int key = 64 * r + lane;
;       u[r] = (key <= t) ? fkey(srow[key]) : 0u;
;     }
.LBB0_413:
	s_or_b64 exec, exec, s[0:1]
	v_cmp_le_i32_e32 vcc, v66, v102
	v_mov_b32_e32 v121, 0
	v_mov_b32_e32 v122, 0
	s_and_saveexec_b64 s[0:1], vcc
	s_cbranch_execz .LBB0_415
	v_lshlrev_b32_e32 v124, 2, v66
	v_mov_b32_e32 v125, v1
	v_lshl_add_u64 v[124:125], v[104:105], 0, v[124:125]
	s_waitcnt vmcnt(15)
	v_mov_b32_e32 v106, v185
	v_not_b32_e32 v122, v106
	v_or_b32_e32 v124, 0x80000000, v106
	v_cmp_gt_i32_e32 vcc, 0, v106
	s_nop 1
	v_cndmask_b32_e32 v122, v124, v122, vcc
.LBB0_415:
	s_or_b64 exec, exec, s[0:1]
	v_cmp_le_i32_e32 vcc, v68, v102
	s_and_saveexec_b64 s[0:1], vcc
	s_cbranch_execz .LBB0_417
	v_lshlrev_b32_e32 v124, 2, v68
	v_mov_b32_e32 v125, v1
	v_lshl_add_u64 v[124:125], v[104:105], 0, v[124:125]
	s_waitcnt vmcnt(14)
	v_mov_b32_e32 v106, v186
	v_not_b32_e32 v121, v106
	v_or_b32_e32 v124, 0x80000000, v106
	v_cmp_gt_i32_e32 vcc, 0, v106
	s_nop 1
	v_cndmask_b32_e32 v121, v124, v121, vcc
.LBB0_417:
	s_or_b64 exec, exec, s[0:1]
	v_cmp_le_i32_e32 vcc, v70, v102
	v_mov_b32_e32 v124, 0
	v_mov_b32_e32 v125, 0
	s_and_saveexec_b64 s[0:1], vcc
	s_cbranch_execz .LBB0_419
	v_lshlrev_b32_e32 v126, 2, v70
	v_mov_b32_e32 v127, v1
	v_lshl_add_u64 v[126:127], v[104:105], 0, v[126:127]
	s_waitcnt vmcnt(13)
	v_mov_b32_e32 v106, v187
	v_not_b32_e32 v125, v106
	v_or_b32_e32 v126, 0x80000000, v106
	v_cmp_gt_i32_e32 vcc, 0, v106
	s_nop 1
	v_cndmask_b32_e32 v125, v126, v125, vcc
.LBB0_419:
	s_or_b64 exec, exec, s[0:1]
	v_cmp_le_i32_e32 vcc, v72, v102
	s_and_saveexec_b64 s[0:1], vcc
	s_cbranch_execz .LBB0_421
	v_lshlrev_b32_e32 v126, 2, v72
	v_mov_b32_e32 v127, v1
	v_lshl_add_u64 v[126:127], v[104:105], 0, v[126:127]
	s_waitcnt vmcnt(12)
	v_mov_b32_e32 v106, v198
	v_not_b32_e32 v124, v106
	v_or_b32_e32 v126, 0x80000000, v106
	v_cmp_gt_i32_e32 vcc, 0, v106
	s_nop 1
	v_cndmask_b32_e32 v124, v126, v124, vcc
.LBB0_421:
	s_or_b64 exec, exec, s[0:1]
	v_cmp_le_i32_e32 vcc, v74, v102
	v_mov_b32_e32 v126, 0
	v_mov_b32_e32 v127, 0
	s_and_saveexec_b64 s[0:1], vcc
	s_cbranch_execz .LBB0_423
	v_lshlrev_b32_e32 v128, 2, v74
	v_mov_b32_e32 v129, v1
	v_lshl_add_u64 v[128:129], v[104:105], 0, v[128:129]
	s_waitcnt vmcnt(11)
	v_mov_b32_e32 v106, v199
	v_not_b32_e32 v127, v106
	v_or_b32_e32 v128, 0x80000000, v106
	v_cmp_gt_i32_e32 vcc, 0, v106
	s_nop 1
	v_cndmask_b32_e32 v127, v128, v127, vcc
.LBB0_423:
	s_or_b64 exec, exec, s[0:1]
	v_cmp_le_i32_e32 vcc, v76, v102
	s_and_saveexec_b64 s[0:1], vcc
	s_cbranch_execz .LBB0_425
	v_lshlrev_b32_e32 v128, 2, v76
	v_mov_b32_e32 v129, v1
	v_lshl_add_u64 v[128:129], v[104:105], 0, v[128:129]
	s_waitcnt vmcnt(10)
	v_mov_b32_e32 v106, v200
	v_not_b32_e32 v126, v106
	v_or_b32_e32 v128, 0x80000000, v106
	v_cmp_gt_i32_e32 vcc, 0, v106
	s_nop 1
	v_cndmask_b32_e32 v126, v128, v126, vcc
.LBB0_425:
	s_or_b64 exec, exec, s[0:1]
	v_cmp_le_i32_e32 vcc, v78, v102
	v_mov_b32_e32 v128, 0
	v_mov_b32_e32 v129, 0
	s_and_saveexec_b64 s[0:1], vcc
	s_cbranch_execz .LBB0_427
	v_lshlrev_b32_e32 v130, 2, v78
	v_mov_b32_e32 v131, v1
	v_lshl_add_u64 v[130:131], v[104:105], 0, v[130:131]
	s_waitcnt vmcnt(9)
	v_mov_b32_e32 v106, v201
	v_not_b32_e32 v129, v106
	v_or_b32_e32 v130, 0x80000000, v106
	v_cmp_gt_i32_e32 vcc, 0, v106
	s_nop 1
	v_cndmask_b32_e32 v129, v130, v129, vcc
.LBB0_427:
	s_or_b64 exec, exec, s[0:1]
	v_cmp_le_i32_e32 vcc, v80, v102
	s_and_saveexec_b64 s[0:1], vcc
	s_cbranch_execz .LBB0_429
	v_lshlrev_b32_e32 v130, 2, v80
	v_mov_b32_e32 v131, v1
	v_lshl_add_u64 v[130:131], v[104:105], 0, v[130:131]
	s_waitcnt vmcnt(8)
	v_mov_b32_e32 v106, v202
	v_not_b32_e32 v128, v106
	v_or_b32_e32 v130, 0x80000000, v106
	v_cmp_gt_i32_e32 vcc, 0, v106
	s_nop 1
	v_cndmask_b32_e32 v128, v130, v128, vcc
; DI u32 fkey(float f) { u32 u = __float_as_uint(f); return (u & 0x80000000u) ? ~u : (u | 0x80000000u); }
; DI void indexer_item(const Params& p, int b, int qt16, char* smem) {
;     ...
;     const float* srow = scr + (long)q * SEQ;
;     u32 u[64];
; #pragma unroll
;     for (int r = 0; r < 64; ++r) {
;       const int key = 64 * r + lane;
;       u[r] = (key <= t) ? fkey(srow[key]) : 0u;
;     }
.LBB0_429:
	s_or_b64 exec, exec, s[0:1]
	v_cmp_le_i32_e32 vcc, v82, v102
	v_mov_b32_e32 v130, 0
	v_mov_b32_e32 v131, 0
	s_and_saveexec_b64 s[0:1], vcc
	s_cbranch_execz .LBB0_431
	v_lshlrev_b32_e32 v132, 2, v82
	v_mov_b32_e32 v133, v1
	v_lshl_add_u64 v[132:133], v[104:105], 0, v[132:133]
	s_waitcnt vmcnt(7)
	v_mov_b32_e32 v106, v203
	v_not_b32_e32 v131, v106
	v_or_b32_e32 v132, 0x80000000, v106
	v_cmp_gt_i32_e32 vcc, 0, v106
	s_nop 1
	v_cndmask_b32_e32 v131, v132, v131, vcc
.LBB0_431:
	s_or_b64 exec, exec, s[0:1]
	v_cmp_le_i32_e32 vcc, v84, v102
	s_and_saveexec_b64 s[0:1], vcc
	s_cbranch_execz .LBB0_433
	v_lshlrev_b32_e32 v132, 2, v84
	v_mov_b32_e32 v133, v1
	v_lshl_add_u64 v[132:133], v[104:105], 0, v[132:133]
	s_waitcnt vmcnt(6)
	v_mov_b32_e32 v106, v204
	v_not_b32_e32 v130, v106
	v_or_b32_e32 v132, 0x80000000, v106
	v_cmp_gt_i32_e32 vcc, 0, v106
	s_nop 1
	v_cndmask_b32_e32 v130, v132, v130, vcc
.LBB0_433:
	s_or_b64 exec, exec, s[0:1]
	v_cmp_le_i32_e32 vcc, v88, v102
	v_mov_b32_e32 v132, 0
	v_mov_b32_e32 v133, 0
	s_and_saveexec_b64 s[0:1], vcc
	s_cbranch_execz .LBB0_435
	v_lshlrev_b32_e32 v134, 2, v88
	v_mov_b32_e32 v135, v1
	v_lshl_add_u64 v[134:135], v[104:105], 0, v[134:135]
	s_waitcnt vmcnt(5)
	v_mov_b32_e32 v106, v205
	v_not_b32_e32 v133, v106
	v_or_b32_e32 v134, 0x80000000, v106
	v_cmp_gt_i32_e32 vcc, 0, v106
	s_nop 1
	v_cndmask_b32_e32 v133, v134, v133, vcc
.LBB0_435:
	s_or_b64 exec, exec, s[0:1]
	v_cmp_le_i32_e32 vcc, v90, v102
	s_and_saveexec_b64 s[0:1], vcc
	s_cbranch_execz .LBB0_437
	v_lshlrev_b32_e32 v134, 2, v90
	v_mov_b32_e32 v135, v1
	v_lshl_add_u64 v[134:135], v[104:105], 0, v[134:135]
	s_waitcnt vmcnt(4)
	v_mov_b32_e32 v106, v206
	v_not_b32_e32 v132, v106
	v_or_b32_e32 v134, 0x80000000, v106
	v_cmp_gt_i32_e32 vcc, 0, v106
	s_nop 1
	v_cndmask_b32_e32 v132, v134, v132, vcc
.LBB0_437:
	s_or_b64 exec, exec, s[0:1]
	v_cmp_le_i32_e32 vcc, v92, v102
	v_mov_b32_e32 v135, 0
	v_mov_b32_e32 v136, 0
	s_and_saveexec_b64 s[0:1], vcc
	s_cbranch_execz .LBB0_439
	v_lshlrev_b32_e32 v136, 2, v92
	v_mov_b32_e32 v137, v1
	v_lshl_add_u64 v[136:137], v[104:105], 0, v[136:137]
	s_waitcnt vmcnt(3)
	v_mov_b32_e32 v106, v207
	v_not_b32_e32 v134, v106
	v_or_b32_e32 v136, 0x80000000, v106
	v_cmp_gt_i32_e32 vcc, 0, v106
	s_nop 1
	v_cndmask_b32_e32 v136, v136, v134, vcc
.LBB0_439:
	s_or_b64 exec, exec, s[0:1]
	v_cmp_le_i32_e32 vcc, v94, v102
	s_and_saveexec_b64 s[0:1], vcc
	s_cbranch_execz .LBB0_441
	v_lshlrev_b32_e32 v134, 2, v94
	v_mov_b32_e32 v135, v1
	v_lshl_add_u64 v[134:135], v[104:105], 0, v[134:135]
	s_waitcnt vmcnt(2)
	v_mov_b32_e32 v106, v210
	v_not_b32_e32 v134, v106
	v_or_b32_e32 v135, 0x80000000, v106
	v_cmp_gt_i32_e32 vcc, 0, v106
	s_nop 1
	v_cndmask_b32_e32 v135, v135, v134, vcc
.LBB0_441:
	s_or_b64 exec, exec, s[0:1]
	v_cmp_le_i32_e32 vcc, v96, v102
	v_mov_b32_e32 v134, 0
	v_mov_b32_e32 v137, 0
	s_and_saveexec_b64 s[0:1], vcc
	s_cbranch_execz .LBB0_443
	v_lshlrev_b32_e32 v138, 2, v96
	v_mov_b32_e32 v139, v1
	v_lshl_add_u64 v[138:139], v[104:105], 0, v[138:139]
	s_waitcnt vmcnt(1)
	v_mov_b32_e32 v106, v211
	v_not_b32_e32 v137, v106
	v_or_b32_e32 v138, 0x80000000, v106
	v_cmp_gt_i32_e32 vcc, 0, v106
	s_nop 1
	v_cndmask_b32_e32 v137, v138, v137, vcc
.LBB0_443:
	s_or_b64 exec, exec, s[0:1]
	v_cmp_le_i32_e32 vcc, v98, v102
	s_and_saveexec_b64 s[0:1], vcc
	s_cbranch_execz .LBB0_445
	v_lshlrev_b32_e32 v138, 2, v98
	v_mov_b32_e32 v139, v1
	v_lshl_add_u64 v[104:105], v[104:105], 0, v[138:139]
	s_waitcnt vmcnt(0)
	v_mov_b32_e32 v104, v212
	v_not_b32_e32 v105, v104
	v_or_b32_e32 v106, 0x80000000, v104
	v_cmp_gt_i32_e32 vcc, 0, v104
	s_nop 1
	v_cndmask_b32_e32 v134, v106, v105, vcc
